# v44 + norm_sample_row slab loads issued before the first wait + prompt-attention K/V staging loads issued up front (v39 change)
# baseline (speedup 1.0000x reference)
.LBB0_1232:
	s_or_b64 exec, exec, s[0:1]
	s_mov_b32 s0, s55
	s_waitcnt lgkmcnt(0)
	s_barrier
	v_mbcnt_lo_u32_b32 v0, -1, 0
	v_mbcnt_hi_u32_b32 v0, -1, v0
	s_mov_b64 s[2:3], -1
	v_lshl_add_u32 v205, s0, 6, v0
	v_and_b32_e32 v204, 63, v0
	v_readfirstlane_b32 s0, v205
	s_ashr_i32 s6, s0, 6
	v_readlane_b32 s0, v254, 11
	v_readlane_b32 s1, v254, 12
	v_lshlrev_b32_e32 v66, 3, v205
	s_andn2_b64 vcc, exec, s[0:1]
	v_cmp_eq_u32_e64 s[0:1], 0, v204
	v_ashrrev_i32_e32 v67, 31, v66
	s_cbranch_vccnz .LBB0_1244
	v_readlane_b32 s2, v254, 3
	v_readlane_b32 s3, v254, 4
	s_nop 1
	v_lshl_add_u64 v[2:3], v[66:67], 0, s[2:3]
	v_readlane_b32 s2, v254, 5
	v_lshlrev_b64 v[2:3], 1, v[2:3]
	v_readlane_b32 s3, v254, 6
	s_nop 1
	v_lshl_add_u64 v[30:31], s[2:3], 0, v[2:3]
	v_readlane_b32 s2, v252, 50
	v_readlane_b32 s3, v252, 51
	s_nop 1
	v_lshl_add_u64 v[6:7], s[2:3], 0, v[2:3]
	v_add_co_u32_e32 v8, vcc, 0x200000, v6
	global_load_dwordx4 v[2:5], v[30:31], off
	global_load_dwordx4 v[32:35], v[6:7], off
	v_addc_co_u32_e32 v9, vcc, 0, v7, vcc
	v_add_co_u32_e32 v10, vcc, 0x400000, v6
	s_nop 1
	v_addc_co_u32_e32 v11, vcc, 0, v7, vcc
	global_load_dwordx4 v[36:39], v[8:9], off
	global_load_dwordx4 v[40:43], v[10:11], off
	v_add_co_u32_e32 v8, vcc, 0x600000, v6
	s_nop 1
	v_addc_co_u32_e32 v9, vcc, 0, v7, vcc
	v_add_co_u32_e32 v10, vcc, 0x800000, v6
	s_nop 1
	v_addc_co_u32_e32 v11, vcc, 0, v7, vcc
	global_load_dwordx4 v[44:47], v[8:9], off
	global_load_dwordx4 v[48:51], v[10:11], off
	v_add_co_u32_e32 v8, vcc, 0xa00000, v6
	s_nop 1
	v_addc_co_u32_e32 v9, vcc, 0, v7, vcc
	v_add_co_u32_e32 v10, vcc, 0xc00000, v6
	s_nop 1
	v_addc_co_u32_e32 v11, vcc, 0, v7, vcc
	global_load_dwordx4 v[52:55], v[8:9], off
	global_load_dwordx4 v[56:59], v[10:11], off
	v_add_co_u32_e32 v8, vcc, 0xe00000, v6
	s_nop 1
	v_addc_co_u32_e32 v9, vcc, 0, v7, vcc
	v_add_co_u32_e32 v10, vcc, 0x1000000, v6
	s_nop 1
	v_addc_co_u32_e32 v11, vcc, 0, v7, vcc
	global_load_dwordx4 v[60:63], v[8:9], off
	global_load_dwordx4 v[68:71], v[10:11], off
	v_add_co_u32_e32 v8, vcc, 0x1200000, v6
	s_nop 1
	v_addc_co_u32_e32 v9, vcc, 0, v7, vcc
	v_add_co_u32_e32 v10, vcc, 0x1400000, v6
	s_nop 1
	v_addc_co_u32_e32 v11, vcc, 0, v7, vcc
	global_load_dwordx4 v[72:75], v[8:9], off
	global_load_dwordx4 v[26:29], v[10:11], off
	v_add_co_u32_e32 v8, vcc, 0x1600000, v6
	s_nop 1
	v_addc_co_u32_e32 v9, vcc, 0, v7, vcc
	v_add_co_u32_e32 v10, vcc, 0x1800000, v6
	s_nop 1
	v_addc_co_u32_e32 v11, vcc, 0, v7, vcc
	global_load_dwordx4 v[22:25], v[8:9], off
	global_load_dwordx4 v[18:21], v[10:11], off
	v_add_co_u32_e32 v8, vcc, 0x1a00000, v6
	s_nop 1
	v_addc_co_u32_e32 v9, vcc, 0, v7, vcc
	v_add_co_u32_e32 v10, vcc, 0x1c00000, v6
	s_nop 1
	v_addc_co_u32_e32 v11, vcc, 0, v7, vcc
	global_load_dwordx4 v[14:17], v[8:9], off
	s_nop 0
	global_load_dwordx4 v[10:13], v[10:11], off
	v_add_co_u32_e32 v6, vcc, 0x1e00000, v6
	s_nop 1
	v_addc_co_u32_e32 v7, vcc, 0, v7, vcc
	global_load_dwordx4 v[6:9], v[6:7], off
	s_waitcnt vmcnt(15)
	v_lshlrev_b32_e32 v64, 16, v32
	v_and_b32_e32 v65, 0xffff0000, v32
	v_lshlrev_b32_e32 v32, 16, v33
	v_and_b32_e32 v33, 0xffff0000, v33
	v_pk_add_f32 v[64:65], v[64:65], 0 op_sel_hi:[1,0]
	v_pk_add_f32 v[32:33], v[32:33], 0 op_sel_hi:[1,0]
	v_lshlrev_b32_e32 v76, 16, v34
	v_and_b32_e32 v77, 0xffff0000, v34
	v_lshlrev_b32_e32 v34, 16, v35
	v_and_b32_e32 v35, 0xffff0000, v35
	v_pk_add_f32 v[76:77], v[76:77], 0 op_sel_hi:[1,0]
	v_pk_add_f32 v[34:35], v[34:35], 0 op_sel_hi:[1,0]
	s_waitcnt vmcnt(14)
	v_lshlrev_b32_e32 v78, 16, v36
	v_and_b32_e32 v79, 0xffff0000, v36
	v_lshlrev_b32_e32 v36, 16, v37
	v_and_b32_e32 v37, 0xffff0000, v37
	v_pk_add_f32 v[32:33], v[32:33], v[36:37]
	v_pk_add_f32 v[36:37], v[64:65], v[78:79]
	v_lshlrev_b32_e32 v64, 16, v38
	v_and_b32_e32 v65, 0xffff0000, v38
	v_lshlrev_b32_e32 v38, 16, v39
	v_and_b32_e32 v39, 0xffff0000, v39
	v_pk_add_f32 v[34:35], v[34:35], v[38:39]
	v_pk_add_f32 v[38:39], v[76:77], v[64:65]
	s_waitcnt vmcnt(13)
	v_lshlrev_b32_e32 v64, 16, v40
	v_and_b32_e32 v65, 0xffff0000, v40
	v_lshlrev_b32_e32 v40, 16, v41
	v_and_b32_e32 v41, 0xffff0000, v41
	v_pk_add_f32 v[32:33], v[32:33], v[40:41]
	v_lshlrev_b32_e32 v40, 16, v42
	v_and_b32_e32 v41, 0xffff0000, v42
	v_pk_add_f32 v[36:37], v[36:37], v[64:65]
	v_lshlrev_b32_e32 v42, 16, v43
	v_and_b32_e32 v43, 0xffff0000, v43
	v_pk_add_f32 v[38:39], v[38:39], v[40:41]
	s_waitcnt vmcnt(12)
	v_lshlrev_b32_e32 v40, 16, v44
	v_and_b32_e32 v41, 0xffff0000, v44
	v_pk_add_f32 v[34:35], v[34:35], v[42:43]
	v_lshlrev_b32_e32 v42, 16, v45
	v_and_b32_e32 v43, 0xffff0000, v45
	v_pk_add_f32 v[36:37], v[36:37], v[40:41]
	v_lshlrev_b32_e32 v40, 16, v46
	v_and_b32_e32 v41, 0xffff0000, v46
	v_pk_add_f32 v[32:33], v[32:33], v[42:43]
	v_lshlrev_b32_e32 v42, 16, v47
	v_and_b32_e32 v43, 0xffff0000, v47
	v_pk_add_f32 v[38:39], v[38:39], v[40:41]
	s_waitcnt vmcnt(11)
	v_lshlrev_b32_e32 v40, 16, v48
	v_and_b32_e32 v41, 0xffff0000, v48
	v_pk_add_f32 v[34:35], v[34:35], v[42:43]
	v_lshlrev_b32_e32 v42, 16, v49
	v_and_b32_e32 v43, 0xffff0000, v49
	v_pk_add_f32 v[36:37], v[36:37], v[40:41]
	v_lshlrev_b32_e32 v40, 16, v50
	v_and_b32_e32 v41, 0xffff0000, v50
	v_pk_add_f32 v[32:33], v[32:33], v[42:43]
	v_lshlrev_b32_e32 v42, 16, v51
	v_and_b32_e32 v43, 0xffff0000, v51
	v_pk_add_f32 v[38:39], v[38:39], v[40:41]
	s_waitcnt vmcnt(10)
	v_lshlrev_b32_e32 v40, 16, v52
	v_and_b32_e32 v41, 0xffff0000, v52
	v_pk_add_f32 v[34:35], v[34:35], v[42:43]
	v_lshlrev_b32_e32 v42, 16, v53
	v_and_b32_e32 v43, 0xffff0000, v53
	v_pk_add_f32 v[36:37], v[36:37], v[40:41]
	v_lshlrev_b32_e32 v40, 16, v54
	v_and_b32_e32 v41, 0xffff0000, v54
	v_pk_add_f32 v[32:33], v[32:33], v[42:43]
	v_lshlrev_b32_e32 v42, 16, v55
	v_and_b32_e32 v43, 0xffff0000, v55
	v_pk_add_f32 v[38:39], v[38:39], v[40:41]
	s_waitcnt vmcnt(9)
	v_lshlrev_b32_e32 v40, 16, v56
	v_and_b32_e32 v41, 0xffff0000, v56
	v_pk_add_f32 v[34:35], v[34:35], v[42:43]
	v_lshlrev_b32_e32 v42, 16, v57
	v_and_b32_e32 v43, 0xffff0000, v57
	v_pk_add_f32 v[36:37], v[36:37], v[40:41]
	v_lshlrev_b32_e32 v40, 16, v58
	v_and_b32_e32 v41, 0xffff0000, v58
	v_pk_add_f32 v[32:33], v[32:33], v[42:43]
	v_lshlrev_b32_e32 v42, 16, v59
	v_and_b32_e32 v43, 0xffff0000, v59
	v_pk_add_f32 v[38:39], v[38:39], v[40:41]
	s_waitcnt vmcnt(8)
	v_lshlrev_b32_e32 v40, 16, v60
	v_and_b32_e32 v41, 0xffff0000, v60
	v_pk_add_f32 v[34:35], v[34:35], v[42:43]
	v_lshlrev_b32_e32 v42, 16, v61
	v_and_b32_e32 v43, 0xffff0000, v61
	v_pk_add_f32 v[36:37], v[36:37], v[40:41]
	v_lshlrev_b32_e32 v40, 16, v62
	v_and_b32_e32 v41, 0xffff0000, v62
	v_pk_add_f32 v[32:33], v[32:33], v[42:43]
	v_lshlrev_b32_e32 v42, 16, v63
	v_and_b32_e32 v43, 0xffff0000, v63
	v_pk_add_f32 v[38:39], v[38:39], v[40:41]
	s_waitcnt vmcnt(7)
	v_lshlrev_b32_e32 v40, 16, v68
	v_and_b32_e32 v41, 0xffff0000, v68
	v_pk_add_f32 v[34:35], v[34:35], v[42:43]
	v_lshlrev_b32_e32 v42, 16, v69
	v_and_b32_e32 v43, 0xffff0000, v69
	v_pk_add_f32 v[36:37], v[36:37], v[40:41]
	v_lshlrev_b32_e32 v40, 16, v70
	v_and_b32_e32 v41, 0xffff0000, v70
	v_pk_add_f32 v[32:33], v[32:33], v[42:43]
	v_lshlrev_b32_e32 v42, 16, v71
	v_and_b32_e32 v43, 0xffff0000, v71
	v_pk_add_f32 v[38:39], v[38:39], v[40:41]
	s_waitcnt vmcnt(6)
	v_lshlrev_b32_e32 v40, 16, v72
	v_and_b32_e32 v41, 0xffff0000, v72
	v_pk_add_f32 v[34:35], v[34:35], v[42:43]
	v_lshlrev_b32_e32 v42, 16, v73
	v_and_b32_e32 v43, 0xffff0000, v73
	v_pk_add_f32 v[36:37], v[36:37], v[40:41]
	v_lshlrev_b32_e32 v40, 16, v74
	v_and_b32_e32 v41, 0xffff0000, v74
	v_pk_add_f32 v[32:33], v[32:33], v[42:43]
	v_lshlrev_b32_e32 v42, 16, v75
	v_and_b32_e32 v43, 0xffff0000, v75
	v_pk_add_f32 v[38:39], v[38:39], v[40:41]
	s_waitcnt vmcnt(5)
	v_lshlrev_b32_e32 v40, 16, v26
	v_and_b32_e32 v41, 0xffff0000, v26
	v_lshlrev_b32_e32 v26, 16, v27
	v_and_b32_e32 v27, 0xffff0000, v27
	v_pk_add_f32 v[34:35], v[34:35], v[42:43]
	v_pk_add_f32 v[26:27], v[32:33], v[26:27]
	v_lshlrev_b32_e32 v32, 16, v28
	v_and_b32_e32 v33, 0xffff0000, v28
	v_lshlrev_b32_e32 v28, 16, v29
	v_and_b32_e32 v29, 0xffff0000, v29
	v_pk_add_f32 v[36:37], v[36:37], v[40:41]
	v_pk_add_f32 v[28:29], v[34:35], v[28:29]
	s_waitcnt vmcnt(4)
	v_lshlrev_b32_e32 v34, 16, v22
	v_and_b32_e32 v35, 0xffff0000, v22
	v_lshlrev_b32_e32 v22, 16, v23
	v_and_b32_e32 v23, 0xffff0000, v23
	v_pk_add_f32 v[32:33], v[38:39], v[32:33]
	v_pk_add_f32 v[22:23], v[26:27], v[22:23]
	v_pk_add_f32 v[26:27], v[36:37], v[34:35]
	v_lshlrev_b32_e32 v34, 16, v24
	v_and_b32_e32 v35, 0xffff0000, v24
	v_lshlrev_b32_e32 v24, 16, v25
	v_and_b32_e32 v25, 0xffff0000, v25
	v_pk_add_f32 v[24:25], v[28:29], v[24:25]
	v_pk_add_f32 v[28:29], v[32:33], v[34:35]
	s_waitcnt vmcnt(3)
	v_lshlrev_b32_e32 v32, 16, v18
	v_and_b32_e32 v33, 0xffff0000, v18
	v_lshlrev_b32_e32 v18, 16, v19
	v_and_b32_e32 v19, 0xffff0000, v19
	v_pk_add_f32 v[18:19], v[22:23], v[18:19]
	v_lshlrev_b32_e32 v22, 16, v20
	v_and_b32_e32 v23, 0xffff0000, v20
	v_lshlrev_b32_e32 v20, 16, v21
	v_and_b32_e32 v21, 0xffff0000, v21
	v_pk_add_f32 v[26:27], v[26:27], v[32:33]
	v_pk_add_f32 v[20:21], v[24:25], v[20:21]
	s_waitcnt vmcnt(2)
	v_lshlrev_b32_e32 v24, 16, v14
	v_and_b32_e32 v25, 0xffff0000, v14
	v_lshlrev_b32_e32 v14, 16, v15
	v_and_b32_e32 v15, 0xffff0000, v15
	v_pk_add_f32 v[22:23], v[28:29], v[22:23]
	v_pk_add_f32 v[14:15], v[18:19], v[14:15]
	v_pk_add_f32 v[18:19], v[26:27], v[24:25]
	v_lshlrev_b32_e32 v24, 16, v16
	v_and_b32_e32 v25, 0xffff0000, v16
	v_lshlrev_b32_e32 v16, 16, v17
	v_and_b32_e32 v17, 0xffff0000, v17
	v_pk_add_f32 v[16:17], v[20:21], v[16:17]
	v_pk_add_f32 v[20:21], v[22:23], v[24:25]
	s_waitcnt vmcnt(1)
	v_lshlrev_b32_e32 v22, 16, v10
	v_and_b32_e32 v23, 0xffff0000, v10
	v_lshlrev_b32_e32 v10, 16, v11
	v_and_b32_e32 v11, 0xffff0000, v11
	v_pk_add_f32 v[10:11], v[14:15], v[10:11]
	v_lshlrev_b32_e32 v14, 16, v12
	v_and_b32_e32 v15, 0xffff0000, v12
	v_lshlrev_b32_e32 v12, 16, v13
	v_and_b32_e32 v13, 0xffff0000, v13
	v_pk_add_f32 v[18:19], v[18:19], v[22:23]
	v_pk_add_f32 v[16:17], v[16:17], v[12:13]
	s_waitcnt vmcnt(0)
	v_lshlrev_b32_e32 v12, 16, v6
	v_and_b32_e32 v13, 0xffff0000, v6
	v_lshlrev_b32_e32 v6, 16, v7
	v_and_b32_e32 v7, 0xffff0000, v7
	v_pk_add_f32 v[14:15], v[20:21], v[14:15]
	v_pk_add_f32 v[10:11], v[10:11], v[6:7]
	v_pk_add_f32 v[12:13], v[18:19], v[12:13]
	v_lshlrev_b32_e32 v18, 16, v8
	v_and_b32_e32 v19, 0xffff0000, v8
	v_lshlrev_b32_e32 v6, 16, v9
	v_and_b32_e32 v7, 0xffff0000, v9
	v_pk_add_f32 v[8:9], v[14:15], v[18:19]
	v_mul_f32_e32 v0, v13, v13
	v_mul_f32_e32 v14, v11, v11
	v_fmac_f32_e32 v0, v12, v12
	v_fmac_f32_e32 v14, v10, v10
	v_add_f32_e32 v0, v0, v14
	v_mul_f32_e32 v14, v9, v9
	v_pk_add_f32 v[6:7], v[16:17], v[6:7]
	v_fmac_f32_e32 v14, v8, v8
	v_add_f32_e32 v0, v14, v0
	v_mul_f32_e32 v14, v7, v7
	v_fmac_f32_e32 v14, v6, v6
	v_add_f32_e32 v0, v14, v0
	ds_swizzle_b32 v14, v0 offset:swizzle(SWAP,1)
	v_ashrrev_i32_e32 v18, 6, v205
	s_waitcnt lgkmcnt(0)
	v_add_f32_e32 v0, v0, v14
	ds_swizzle_b32 v14, v0 offset:swizzle(SWAP,2)
	s_waitcnt lgkmcnt(0)
	v_add_f32_e32 v0, v0, v14
	ds_swizzle_b32 v14, v0 offset:swizzle(SWAP,4)
	s_waitcnt lgkmcnt(0)
	v_add_f32_e32 v0, v0, v14
	ds_swizzle_b32 v14, v0 offset:swizzle(SWAP,8)
	s_waitcnt lgkmcnt(0)
	v_add_f32_e32 v0, v0, v14
	ds_swizzle_b32 v14, v0 offset:swizzle(SWAP,16)
	s_waitcnt lgkmcnt(0)
	v_add_f32_e32 v0, v0, v14
	s_nop 0
	v_readlane_b32 s4, v0, 0
	v_readlane_b32 s5, v0, 32
	s_and_saveexec_b64 s[2:3], s[0:1]
	s_nop 0
	v_mov_b32_e32 v0, s5
	v_lshl_add_u32 v14, v18, 2, 0
	v_add_f32_e32 v0, s4, v0
	v_add_u32_e32 v14, 0x14000, v14
	ds_write_b32 v14, v0
	s_or_b64 exec, exec, s[2:3]
	v_mov_b32_e32 v0, s54
	s_waitcnt lgkmcnt(0)
	s_barrier
	ds_read_b128 v[20:23], v0
	v_readlane_b32 s4, v255, 42
	v_readlane_b32 s16, v252, 28
	v_readlane_b32 s28, v252, 40
	v_mov_b32_e32 v19, s4
	s_waitcnt lgkmcnt(0)
	v_add_f32_e32 v0, 0, v20
	v_add_f32_e32 v0, v0, v21
	v_add_f32_e32 v0, v0, v22
	v_add_f32_e32 v0, v0, v23
	ds_read_b128 v[20:23], v19
	v_readlane_b32 s2, v254, 17
	v_readlane_b32 s29, v252, 41
	v_readlane_b32 s3, v254, 18
	s_add_u32 s2, s28, s2
	s_waitcnt lgkmcnt(0)
	v_add_f32_e32 v0, v0, v20
	v_add_f32_e32 v0, v0, v21
	v_add_f32_e32 v0, v0, v22
	v_add_f32_e32 v0, v0, v23
	v_fmamk_f32 v0, v0, 0x39800000, v211
	v_cmp_gt_f32_e32 vcc, s94, v0
	v_mul_f32_e32 v19, 0x4f800000, v0
	s_addc_u32 s3, s29, s3
	v_cndmask_b32_e32 v0, v0, v19, vcc
	v_sqrt_f32_e32 v19, v0
	v_lshl_add_u64 v[24:25], v[66:67], 2, s[2:3]
	v_lshlrev_b32_e32 v14, 16, v2
	v_and_b32_e32 v15, 0xffff0000, v2
	v_add_u32_e32 v20, -1, v19
	v_fma_f32 v21, -v20, v19, v0
	v_cmp_ge_f32_e64 s[4:5], 0, v21
	v_add_u32_e32 v21, 1, v19
	v_lshlrev_b32_e32 v16, 16, v3
	v_cndmask_b32_e64 v20, v19, v20, s[4:5]
	v_fma_f32 v19, -v21, v19, v0
	v_cmp_lt_f32_e64 s[4:5], 0, v19
	v_and_b32_e32 v17, 0xffff0000, v3
	v_lshlrev_b32_e32 v2, 16, v4
	v_cndmask_b32_e64 v19, v20, v21, s[4:5]
	v_mul_f32_e32 v20, 0x37800000, v19
	v_cndmask_b32_e32 v19, v19, v20, vcc
	v_cmp_class_f32_e32 vcc, v0, v212
	v_and_b32_e32 v3, 0xffff0000, v4
	v_lshlrev_b32_e32 v4, 16, v5
	v_cndmask_b32_e32 v0, v19, v0, vcc
	v_div_scale_f32 v19, s[4:5], v0, v0, 1.0
	v_rcp_f32_e32 v20, v19
	v_and_b32_e32 v5, 0xffff0000, v5
	v_readlane_b32 s17, v252, 29
	v_readlane_b32 s18, v252, 30
	v_fma_f32 v21, -v19, v20, 1.0
	v_fmac_f32_e32 v20, v21, v20
	v_div_scale_f32 v21, vcc, 1.0, v0, 1.0
	v_mul_f32_e32 v22, v21, v20
	v_fma_f32 v23, -v19, v22, v21
	v_fmac_f32_e32 v22, v23, v20
	v_fma_f32 v19, -v19, v22, v21
	v_div_fmas_f32 v19, v19, v20, v22
	global_load_dwordx4 v[20:23], v[24:25], off offset:16
	s_nop 0
	global_load_dwordx4 v[24:27], v[24:25], off
	v_div_fixup_f32 v0, v19, v0, 1.0
	v_pk_mul_f32 v[12:13], v[12:13], v[0:1] op_sel_hi:[1,0]
	v_pk_mul_f32 v[10:11], v[10:11], v[0:1] op_sel_hi:[1,0]
	v_pk_mul_f32 v[8:9], v[8:9], v[0:1] op_sel_hi:[1,0]
	v_pk_mul_f32 v[6:7], v[6:7], v[0:1] op_sel_hi:[1,0]
	v_readlane_b32 s19, v252, 31
	v_readlane_b32 s20, v252, 32
	v_readlane_b32 s21, v252, 33
	v_readlane_b32 s22, v252, 34
	v_readlane_b32 s23, v252, 35
	v_readlane_b32 s24, v252, 36
	v_readlane_b32 s25, v252, 37
	v_readlane_b32 s26, v252, 38
	v_readlane_b32 s27, v252, 39
	v_readlane_b32 s30, v252, 42
	v_readlane_b32 s31, v252, 43
	s_waitcnt vmcnt(1)
	v_pk_fma_f32 v[8:9], v[20:21], v[8:9], v[2:3]
	s_waitcnt vmcnt(0)
	v_pk_fma_f32 v[10:11], v[26:27], v[10:11], v[16:17]
	v_pk_fma_f32 v[12:13], v[24:25], v[12:13], v[14:15]
	v_pk_fma_f32 v[6:7], v[22:23], v[6:7], v[4:5]
	v_cvt_pk_bf16_f32 v2, v12, v13
	v_cvt_pk_bf16_f32 v3, v10, v11
	v_cvt_pk_bf16_f32 v4, v8, v9
	v_mul_f32_e32 v0, v13, v13
	v_cvt_pk_bf16_f32 v5, v6, v7
	global_store_dwordx4 v[30:31], v[2:5], off
	v_fmac_f32_e32 v0, v12, v12
	s_nop 0
	v_mul_f32_e32 v2, v11, v11
	v_fmac_f32_e32 v2, v10, v10
	v_add_f32_e32 v0, v0, v2
	v_mul_f32_e32 v2, v9, v9
	v_fmac_f32_e32 v2, v8, v8
	v_add_f32_e32 v0, v2, v0
	v_mul_f32_e32 v2, v7, v7
	v_fmac_f32_e32 v2, v6, v6
	v_add_f32_e32 v0, v2, v0
	ds_swizzle_b32 v2, v0 offset:swizzle(SWAP,1)
	s_waitcnt lgkmcnt(0)
	v_add_f32_e32 v0, v0, v2
	ds_swizzle_b32 v2, v0 offset:swizzle(SWAP,2)
	s_waitcnt lgkmcnt(0)
	v_add_f32_e32 v0, v0, v2
	ds_swizzle_b32 v2, v0 offset:swizzle(SWAP,4)
	s_waitcnt lgkmcnt(0)
	v_add_f32_e32 v0, v0, v2
	ds_swizzle_b32 v2, v0 offset:swizzle(SWAP,8)
	s_waitcnt lgkmcnt(0)
	v_add_f32_e32 v0, v0, v2
	ds_swizzle_b32 v2, v0 offset:swizzle(SWAP,16)
	s_waitcnt lgkmcnt(0)
	v_add_f32_e32 v0, v0, v2
	s_nop 0
	v_readlane_b32 s7, v0, 0
	v_readlane_b32 s8, v0, 32
	s_and_saveexec_b64 s[4:5], s[0:1]
	s_nop 0
	v_mov_b32_e32 v0, s8
	v_add_f32_e32 v0, s7, v0
	v_lshl_add_u32 v2, v18, 2, s54
	ds_write_b32 v2, v0 offset:32
	s_or_b64 exec, exec, s[4:5]
	v_cmp_eq_u32_e32 vcc, 0, v205
	s_waitcnt lgkmcnt(0)
	s_barrier
	s_and_saveexec_b64 s[4:5], vcc
	s_cbranch_execz .LBB0_1239
	v_readlane_b32 s0, v255, 43
	s_nop 1
	v_mov_b32_e32 v0, s0
	ds_read_b128 v[2:5], v0
	v_readlane_b32 s0, v255, 44
	s_waitcnt lgkmcnt(0)
	v_add_f32_e32 v0, 0, v2
	v_add_f32_e32 v0, v0, v3
	v_add_f32_e32 v0, v0, v4
	v_mov_b32_e32 v2, s0
	v_add_f32_e32 v0, v0, v5
	ds_read_b128 v[2:5], v2
	s_waitcnt lgkmcnt(0)
	v_add_f32_e32 v0, v0, v2
	v_add_f32_e32 v0, v0, v3
	v_add_f32_e32 v0, v0, v4
	v_add_f32_e32 v0, v0, v5
	v_fmamk_f32 v0, v0, 0x39800000, v211
	v_cmp_gt_f32_e32 vcc, s94, v0
	v_mul_f32_e32 v2, 0x4f800000, v0
	s_nop 0
	v_cndmask_b32_e32 v0, v0, v2, vcc
	v_sqrt_f32_e32 v2, v0
	s_nop 0
	v_add_u32_e32 v3, -1, v2
	v_fma_f32 v4, -v3, v2, v0
	v_cmp_ge_f32_e64 s[0:1], 0, v4
	v_add_u32_e32 v4, 1, v2
	s_nop 0
	v_cndmask_b32_e64 v3, v2, v3, s[0:1]
	v_fma_f32 v2, -v4, v2, v0
	v_cmp_lt_f32_e64 s[0:1], 0, v2
	s_nop 1
	v_cndmask_b32_e64 v2, v3, v4, s[0:1]
	v_mul_f32_e32 v3, 0x37800000, v2
	v_cndmask_b32_e32 v2, v2, v3, vcc
	v_cmp_class_f32_e32 vcc, v0, v212
	s_nop 1
	v_cndmask_b32_e32 v0, v2, v0, vcc
	v_div_scale_f32 v2, s[0:1], v0, v0, 1.0
	v_rcp_f32_e32 v3, v2
	v_readlane_b32 s0, v254, 9
	v_readlane_b32 s1, v254, 10
	v_fma_f32 v4, -v2, v3, 1.0
	v_fmac_f32_e32 v3, v4, v3
	v_div_scale_f32 v4, vcc, 1.0, v0, 1.0
	v_mul_f32_e32 v5, v4, v3
	v_fma_f32 v6, -v2, v5, v4
	v_fmac_f32_e32 v5, v6, v3
	v_fma_f32 v2, -v2, v5, v4
	v_div_fmas_f32 v2, v2, v3, v5
	v_div_fixup_f32 v0, v2, v0, 1.0
	global_store_dword v1, v0, s[0:1]

.LBB0_1244:
	s_and_b64 vcc, exec, s[2:3]
	s_cbranch_vccz .LBB0_1249
	v_readlane_b32 s0, v254, 3
	v_readlane_b32 s1, v254, 4
	s_nop 1
	v_lshl_add_u64 v[30:31], v[66:67], 0, s[0:1]
	v_readlane_b32 s0, v254, 5
	v_lshlrev_b64 v[2:3], 1, v[30:31]
	v_readlane_b32 s1, v254, 6
	s_nop 1
	v_lshl_add_u64 v[4:5], s[0:1], 0, v[2:3]
	v_readlane_b32 s0, v252, 50
	v_readlane_b32 s1, v252, 51
	s_nop 1
	v_lshl_add_u64 v[6:7], s[0:1], 0, v[2:3]
	v_add_co_u32_e32 v8, vcc, 0x200000, v6
	global_load_dwordx4 v[2:5], v[4:5], off
	s_nop 0
	global_load_dwordx4 v[32:35], v[6:7], off
	v_addc_co_u32_e32 v9, vcc, 0, v7, vcc
	v_add_co_u32_e32 v10, vcc, 0x400000, v6
	s_nop 1
	v_addc_co_u32_e32 v11, vcc, 0, v7, vcc
	global_load_dwordx4 v[36:39], v[8:9], off
	global_load_dwordx4 v[40:43], v[10:11], off
	v_add_co_u32_e32 v8, vcc, 0x600000, v6
	s_nop 1
	v_addc_co_u32_e32 v9, vcc, 0, v7, vcc
	v_add_co_u32_e32 v10, vcc, 0x800000, v6
	s_nop 1
	v_addc_co_u32_e32 v11, vcc, 0, v7, vcc
	global_load_dwordx4 v[44:47], v[8:9], off
	global_load_dwordx4 v[48:51], v[10:11], off
	v_add_co_u32_e32 v8, vcc, 0xa00000, v6
	s_nop 1
	v_addc_co_u32_e32 v9, vcc, 0, v7, vcc
	v_add_co_u32_e32 v10, vcc, 0xc00000, v6
	s_nop 1
	v_addc_co_u32_e32 v11, vcc, 0, v7, vcc
	global_load_dwordx4 v[52:55], v[8:9], off
	global_load_dwordx4 v[56:59], v[10:11], off
	v_add_co_u32_e32 v8, vcc, 0xe00000, v6
	s_nop 1
	v_addc_co_u32_e32 v9, vcc, 0, v7, vcc
	v_add_co_u32_e32 v10, vcc, 0x1000000, v6
	s_nop 1
	v_addc_co_u32_e32 v11, vcc, 0, v7, vcc
	global_load_dwordx4 v[60:63], v[8:9], off
	global_load_dwordx4 v[68:71], v[10:11], off
	v_add_co_u32_e32 v8, vcc, 0x1200000, v6
	s_nop 1
	v_addc_co_u32_e32 v9, vcc, 0, v7, vcc
	v_add_co_u32_e32 v10, vcc, 0x1400000, v6
	s_nop 1
	v_addc_co_u32_e32 v11, vcc, 0, v7, vcc
	global_load_dwordx4 v[72:75], v[8:9], off
	global_load_dwordx4 v[26:29], v[10:11], off
	v_add_co_u32_e32 v8, vcc, 0x1600000, v6
	s_nop 1
	v_addc_co_u32_e32 v9, vcc, 0, v7, vcc
	v_add_co_u32_e32 v10, vcc, 0x1800000, v6
	s_nop 1
	v_addc_co_u32_e32 v11, vcc, 0, v7, vcc
	global_load_dwordx4 v[22:25], v[8:9], off
	global_load_dwordx4 v[18:21], v[10:11], off
	v_add_co_u32_e32 v8, vcc, 0x1a00000, v6
	s_nop 1
	v_addc_co_u32_e32 v9, vcc, 0, v7, vcc
	v_add_co_u32_e32 v10, vcc, 0x1c00000, v6
	s_nop 1
	v_addc_co_u32_e32 v11, vcc, 0, v7, vcc
	global_load_dwordx4 v[14:17], v[8:9], off
	s_nop 0
	global_load_dwordx4 v[10:13], v[10:11], off
	v_add_co_u32_e32 v6, vcc, 0x1e00000, v6
	s_nop 1
	v_addc_co_u32_e32 v7, vcc, 0, v7, vcc
	global_load_dwordx4 v[6:9], v[6:7], off
	s_waitcnt vmcnt(15)
	v_lshlrev_b32_e32 v64, 16, v32
	v_and_b32_e32 v65, 0xffff0000, v32
	v_lshlrev_b32_e32 v32, 16, v33
	v_and_b32_e32 v33, 0xffff0000, v33
	v_pk_add_f32 v[64:65], v[64:65], 0 op_sel_hi:[1,0]
	v_pk_add_f32 v[32:33], v[32:33], 0 op_sel_hi:[1,0]
	v_lshlrev_b32_e32 v76, 16, v34
	v_and_b32_e32 v77, 0xffff0000, v34
	v_lshlrev_b32_e32 v34, 16, v35
	v_and_b32_e32 v35, 0xffff0000, v35
	v_pk_add_f32 v[76:77], v[76:77], 0 op_sel_hi:[1,0]
	v_pk_add_f32 v[34:35], v[34:35], 0 op_sel_hi:[1,0]
	s_waitcnt vmcnt(14)
	v_lshlrev_b32_e32 v78, 16, v36
	v_and_b32_e32 v79, 0xffff0000, v36
	v_lshlrev_b32_e32 v36, 16, v37
	v_and_b32_e32 v37, 0xffff0000, v37
	v_pk_add_f32 v[32:33], v[32:33], v[36:37]
	v_pk_add_f32 v[36:37], v[64:65], v[78:79]
	v_lshlrev_b32_e32 v64, 16, v38
	v_and_b32_e32 v65, 0xffff0000, v38
	v_lshlrev_b32_e32 v38, 16, v39
	v_and_b32_e32 v39, 0xffff0000, v39
	v_pk_add_f32 v[34:35], v[34:35], v[38:39]
	v_pk_add_f32 v[38:39], v[76:77], v[64:65]
	s_waitcnt vmcnt(13)
	v_lshlrev_b32_e32 v64, 16, v40
	v_and_b32_e32 v65, 0xffff0000, v40
	v_lshlrev_b32_e32 v40, 16, v41
	v_and_b32_e32 v41, 0xffff0000, v41
	v_pk_add_f32 v[32:33], v[32:33], v[40:41]
	v_lshlrev_b32_e32 v40, 16, v42
	v_and_b32_e32 v41, 0xffff0000, v42
	v_pk_add_f32 v[36:37], v[36:37], v[64:65]
	v_lshlrev_b32_e32 v42, 16, v43
	v_and_b32_e32 v43, 0xffff0000, v43
	v_pk_add_f32 v[38:39], v[38:39], v[40:41]
	s_waitcnt vmcnt(12)
	v_lshlrev_b32_e32 v40, 16, v44
	v_and_b32_e32 v41, 0xffff0000, v44
	v_pk_add_f32 v[34:35], v[34:35], v[42:43]
	v_lshlrev_b32_e32 v42, 16, v45
	v_and_b32_e32 v43, 0xffff0000, v45
	v_pk_add_f32 v[36:37], v[36:37], v[40:41]
	v_lshlrev_b32_e32 v40, 16, v46
	v_and_b32_e32 v41, 0xffff0000, v46
	v_pk_add_f32 v[32:33], v[32:33], v[42:43]
	v_lshlrev_b32_e32 v42, 16, v47
	v_and_b32_e32 v43, 0xffff0000, v47
	v_pk_add_f32 v[38:39], v[38:39], v[40:41]
	s_waitcnt vmcnt(11)
	v_lshlrev_b32_e32 v40, 16, v48
	v_and_b32_e32 v41, 0xffff0000, v48
	v_pk_add_f32 v[34:35], v[34:35], v[42:43]
	v_lshlrev_b32_e32 v42, 16, v49
	v_and_b32_e32 v43, 0xffff0000, v49
	v_pk_add_f32 v[36:37], v[36:37], v[40:41]
	v_lshlrev_b32_e32 v40, 16, v50
	v_and_b32_e32 v41, 0xffff0000, v50
	v_pk_add_f32 v[32:33], v[32:33], v[42:43]
	v_lshlrev_b32_e32 v42, 16, v51
	v_and_b32_e32 v43, 0xffff0000, v51
	v_pk_add_f32 v[38:39], v[38:39], v[40:41]
	s_waitcnt vmcnt(10)
	v_lshlrev_b32_e32 v40, 16, v52
	v_and_b32_e32 v41, 0xffff0000, v52
	v_pk_add_f32 v[34:35], v[34:35], v[42:43]
	v_lshlrev_b32_e32 v42, 16, v53
	v_and_b32_e32 v43, 0xffff0000, v53
	v_pk_add_f32 v[36:37], v[36:37], v[40:41]
	v_lshlrev_b32_e32 v40, 16, v54
	v_and_b32_e32 v41, 0xffff0000, v54
	v_pk_add_f32 v[32:33], v[32:33], v[42:43]
	v_lshlrev_b32_e32 v42, 16, v55
	v_and_b32_e32 v43, 0xffff0000, v55
	v_pk_add_f32 v[38:39], v[38:39], v[40:41]
	s_waitcnt vmcnt(9)
	v_lshlrev_b32_e32 v40, 16, v56
	v_and_b32_e32 v41, 0xffff0000, v56
	v_pk_add_f32 v[34:35], v[34:35], v[42:43]
	v_lshlrev_b32_e32 v42, 16, v57
	v_and_b32_e32 v43, 0xffff0000, v57
	v_pk_add_f32 v[36:37], v[36:37], v[40:41]
	v_lshlrev_b32_e32 v40, 16, v58
	v_and_b32_e32 v41, 0xffff0000, v58
	v_pk_add_f32 v[32:33], v[32:33], v[42:43]
	v_lshlrev_b32_e32 v42, 16, v59
	v_and_b32_e32 v43, 0xffff0000, v59
	v_pk_add_f32 v[38:39], v[38:39], v[40:41]
	s_waitcnt vmcnt(8)
	v_lshlrev_b32_e32 v40, 16, v60
	v_and_b32_e32 v41, 0xffff0000, v60
	v_pk_add_f32 v[34:35], v[34:35], v[42:43]
	v_lshlrev_b32_e32 v42, 16, v61
	v_and_b32_e32 v43, 0xffff0000, v61
	v_pk_add_f32 v[36:37], v[36:37], v[40:41]
	v_lshlrev_b32_e32 v40, 16, v62
	v_and_b32_e32 v41, 0xffff0000, v62
	v_pk_add_f32 v[32:33], v[32:33], v[42:43]
	v_lshlrev_b32_e32 v42, 16, v63
	v_and_b32_e32 v43, 0xffff0000, v63
	v_pk_add_f32 v[38:39], v[38:39], v[40:41]
	s_waitcnt vmcnt(7)
	v_lshlrev_b32_e32 v40, 16, v68
	v_and_b32_e32 v41, 0xffff0000, v68
	v_pk_add_f32 v[34:35], v[34:35], v[42:43]
	v_lshlrev_b32_e32 v42, 16, v69
	v_and_b32_e32 v43, 0xffff0000, v69
	v_pk_add_f32 v[36:37], v[36:37], v[40:41]
	v_lshlrev_b32_e32 v40, 16, v70
	v_and_b32_e32 v41, 0xffff0000, v70
	v_pk_add_f32 v[32:33], v[32:33], v[42:43]
	v_lshlrev_b32_e32 v42, 16, v71
	v_and_b32_e32 v43, 0xffff0000, v71
	v_pk_add_f32 v[38:39], v[38:39], v[40:41]
	s_waitcnt vmcnt(6)
	v_lshlrev_b32_e32 v40, 16, v72
	v_and_b32_e32 v41, 0xffff0000, v72
	v_pk_add_f32 v[34:35], v[34:35], v[42:43]
	v_lshlrev_b32_e32 v42, 16, v73
	v_and_b32_e32 v43, 0xffff0000, v73
	v_pk_add_f32 v[36:37], v[36:37], v[40:41]
	v_lshlrev_b32_e32 v40, 16, v74
	v_and_b32_e32 v41, 0xffff0000, v74
	v_pk_add_f32 v[32:33], v[32:33], v[42:43]
	v_lshlrev_b32_e32 v42, 16, v75
	v_and_b32_e32 v43, 0xffff0000, v75
	v_pk_add_f32 v[38:39], v[38:39], v[40:41]
	s_waitcnt vmcnt(5)
	v_lshlrev_b32_e32 v40, 16, v26
	v_and_b32_e32 v41, 0xffff0000, v26
	v_lshlrev_b32_e32 v26, 16, v27
	v_and_b32_e32 v27, 0xffff0000, v27
	v_pk_add_f32 v[34:35], v[34:35], v[42:43]
	v_pk_add_f32 v[26:27], v[32:33], v[26:27]
	v_lshlrev_b32_e32 v32, 16, v28
	v_and_b32_e32 v33, 0xffff0000, v28
	v_lshlrev_b32_e32 v28, 16, v29
	v_and_b32_e32 v29, 0xffff0000, v29
	v_pk_add_f32 v[36:37], v[36:37], v[40:41]
	v_pk_add_f32 v[28:29], v[34:35], v[28:29]
	s_waitcnt vmcnt(4)
	v_lshlrev_b32_e32 v34, 16, v22
	v_and_b32_e32 v35, 0xffff0000, v22
	v_lshlrev_b32_e32 v22, 16, v23
	v_and_b32_e32 v23, 0xffff0000, v23
	v_pk_add_f32 v[32:33], v[38:39], v[32:33]
	v_pk_add_f32 v[22:23], v[26:27], v[22:23]
	v_pk_add_f32 v[26:27], v[36:37], v[34:35]
	v_lshlrev_b32_e32 v34, 16, v24
	v_and_b32_e32 v35, 0xffff0000, v24
	v_lshlrev_b32_e32 v24, 16, v25
	v_and_b32_e32 v25, 0xffff0000, v25
	v_pk_add_f32 v[24:25], v[28:29], v[24:25]
	v_pk_add_f32 v[28:29], v[32:33], v[34:35]
	s_waitcnt vmcnt(3)
	v_lshlrev_b32_e32 v32, 16, v18
	v_and_b32_e32 v33, 0xffff0000, v18
	v_lshlrev_b32_e32 v18, 16, v19
	v_and_b32_e32 v19, 0xffff0000, v19
	v_pk_add_f32 v[18:19], v[22:23], v[18:19]
	v_lshlrev_b32_e32 v22, 16, v20
	v_and_b32_e32 v23, 0xffff0000, v20
	v_lshlrev_b32_e32 v20, 16, v21
	v_and_b32_e32 v21, 0xffff0000, v21
	v_pk_add_f32 v[26:27], v[26:27], v[32:33]
	v_pk_add_f32 v[20:21], v[24:25], v[20:21]
	s_waitcnt vmcnt(2)
	v_lshlrev_b32_e32 v24, 16, v14
	v_and_b32_e32 v25, 0xffff0000, v14
	v_lshlrev_b32_e32 v14, 16, v15
	v_and_b32_e32 v15, 0xffff0000, v15
	v_pk_add_f32 v[22:23], v[28:29], v[22:23]
	v_pk_add_f32 v[14:15], v[18:19], v[14:15]
	v_pk_add_f32 v[18:19], v[26:27], v[24:25]
	v_lshlrev_b32_e32 v24, 16, v16
	v_and_b32_e32 v25, 0xffff0000, v16
	v_lshlrev_b32_e32 v16, 16, v17
	v_and_b32_e32 v17, 0xffff0000, v17
	v_pk_add_f32 v[16:17], v[20:21], v[16:17]
	v_pk_add_f32 v[20:21], v[22:23], v[24:25]
	s_waitcnt vmcnt(1)
	v_lshlrev_b32_e32 v22, 16, v10
	v_and_b32_e32 v23, 0xffff0000, v10
	v_lshlrev_b32_e32 v10, 16, v11
	v_and_b32_e32 v11, 0xffff0000, v11
	v_pk_add_f32 v[10:11], v[14:15], v[10:11]
	v_lshlrev_b32_e32 v14, 16, v12
	v_and_b32_e32 v15, 0xffff0000, v12
	v_lshlrev_b32_e32 v12, 16, v13
	v_and_b32_e32 v13, 0xffff0000, v13
	v_pk_add_f32 v[18:19], v[18:19], v[22:23]
	v_pk_add_f32 v[12:13], v[16:17], v[12:13]
	s_waitcnt vmcnt(0)
	v_lshlrev_b32_e32 v16, 16, v6
	v_and_b32_e32 v17, 0xffff0000, v6
	v_lshlrev_b32_e32 v6, 16, v7
	v_and_b32_e32 v7, 0xffff0000, v7
	v_pk_add_f32 v[14:15], v[20:21], v[14:15]
	v_pk_add_f32 v[6:7], v[10:11], v[6:7]
	v_pk_add_f32 v[10:11], v[18:19], v[16:17]
	v_lshlrev_b32_e32 v16, 16, v8
	v_and_b32_e32 v17, 0xffff0000, v8
	v_lshlrev_b32_e32 v8, 16, v9
	v_and_b32_e32 v9, 0xffff0000, v9
	v_pk_add_f32 v[8:9], v[12:13], v[8:9]
	v_pk_add_f32 v[12:13], v[14:15], v[16:17]
	v_mul_f32_e32 v0, v11, v11
	v_mul_f32_e32 v14, v7, v7
	v_fmac_f32_e32 v0, v10, v10
	v_fmac_f32_e32 v14, v6, v6
	v_add_f32_e32 v0, v0, v14
	v_mul_f32_e32 v14, v13, v13
	v_fmac_f32_e32 v14, v12, v12
	v_add_f32_e32 v0, v14, v0
	v_mul_f32_e32 v14, v9, v9
	v_fmac_f32_e32 v14, v8, v8
	v_add_f32_e32 v0, v14, v0
	ds_swizzle_b32 v14, v0 offset:swizzle(SWAP,1)
	v_cmp_eq_u32_e32 vcc, 0, v204
	s_waitcnt lgkmcnt(0)
	v_add_f32_e32 v0, v0, v14
	ds_swizzle_b32 v14, v0 offset:swizzle(SWAP,2)
	s_waitcnt lgkmcnt(0)
	v_add_f32_e32 v0, v0, v14
	ds_swizzle_b32 v14, v0 offset:swizzle(SWAP,4)
	s_waitcnt lgkmcnt(0)
	v_add_f32_e32 v0, v0, v14
	ds_swizzle_b32 v14, v0 offset:swizzle(SWAP,8)
	s_waitcnt lgkmcnt(0)
	v_add_f32_e32 v0, v0, v14
	ds_swizzle_b32 v14, v0 offset:swizzle(SWAP,16)
	s_waitcnt lgkmcnt(0)
	v_add_f32_e32 v0, v0, v14
	s_nop 0
	v_readlane_b32 s2, v0, 0
	v_readlane_b32 s3, v0, 32
	s_and_saveexec_b64 s[0:1], vcc
	s_cbranch_execz .LBB0_1247
	v_ashrrev_i32_e32 v14, 4, v205
	v_mov_b32_e32 v0, s3
	v_add_u32_e32 v14, 0, v14
	v_add_f32_e32 v0, s2, v0
	v_add_u32_e32 v14, 0x14000, v14
	ds_write_b32 v14, v0
